# P4 EpiWo epilogue: x rows loaded three rows ahead with counted vmcnt (no per-row store drain); P3b EpiMerge batched gate loads
# speedup vs baseline: 1.0216x; 1.0052x over previous
.LBB0_746:
	v_lshl_add_u32 v172, s84, 8, v180
	v_lshl_or_b32 v173, s83, 8, v182
	v_xor_b32_e32 v176, 16, v207
	v_xor_b32_e32 v177, 32, v207
	v_lshlrev_b32_e32 v175, 10, v172
	v_add_u32_e32 v175, v175, v173
	v_lshlrev_b32_e32 v174, 2, v175
	v_lshlrev_b32_e32 v175, 1, v175
	v_lshlrev_b32_e32 v173, 2, v173
	v_lshlrev_b32_e32 v172, 2, v172
	v_lshlrev_b32_e32 v176, 2, v176
	v_lshlrev_b32_e32 v177, 2, v177
	global_load_dwordx4 v[62:65], v173, s[4:5]
	global_load_dwordx4 v[58:61], v173, s[4:5] offset:16
	global_load_dwordx4 v[46:49], v173, s[4:5] offset:512
	global_load_dwordx4 v[34:37], v173, s[4:5] offset:528
	global_load_dwordx4 v[212:215], v174, s[2:3]
	global_load_dwordx4 v[216:219], v174, s[2:3] offset:16
	global_load_dwordx4 v[220:223], v174, s[2:3] offset:512
	global_load_dwordx4 v[224:227], v174, s[2:3] offset:528
	s_add_u32 s86, s2, 0x10000
	s_addc_u32 s87, s3, 0
	global_load_dwordx4 v[228:231], v174, s[86:87]
	global_load_dwordx4 v[232:235], v174, s[86:87] offset:16
	global_load_dwordx4 v[236:239], v174, s[86:87] offset:512
	global_load_dwordx4 v[240:243], v174, s[86:87] offset:528
	s_add_u32 s86, s2, 0x20000
	s_addc_u32 s87, s3, 0
	global_load_dwordx4 v[184:187], v174, s[86:87]
	global_load_dwordx4 v[188:191], v174, s[86:87] offset:16
	global_load_dwordx4 v[192:195], v174, s[86:87] offset:512
	global_load_dwordx4 v[244:247], v174, s[86:87] offset:528
	s_lshl_b32 s13, s83, 2
	s_or_b32 s50, s13, s78
	s_ashr_i32 s51, s50, 31
	s_lshl_b64 s[50:51], s[50:51], 17
	v_readlane_b32 s60, v251, 55
	v_readlane_b32 s61, v251, 56
	s_nop 3
	s_add_u32 s50, s60, s50
	s_addc_u32 s51, s61, s51
	s_waitcnt vmcnt(8)
	v_pk_add_f32 v[142:143], v[142:143], v[212:213]
	v_pk_add_f32 v[144:145], v[144:145], v[214:215]
	v_pk_add_f32 v[138:139], v[138:139], v[216:217]
	v_pk_add_f32 v[140:141], v[140:141], v[218:219]
	v_pk_add_f32 v[134:135], v[134:135], v[220:221]
	v_pk_add_f32 v[136:137], v[136:137], v[222:223]
	v_pk_add_f32 v[130:131], v[130:131], v[224:225]
	v_pk_add_f32 v[132:133], v[132:133], v[226:227]
	global_store_dwordx4 v174, v[142:145], s[16:17]
	global_store_dwordx4 v174, v[138:141], s[16:17] offset:16
	global_store_dwordx4 v174, v[134:137], s[16:17] offset:512
	global_store_dwordx4 v174, v[130:133], s[16:17] offset:528
	v_mul_f32_e32 v149, v145, v145
	v_mul_f32_e32 v148, v143, v143
	v_fmac_f32_e32 v148, v142, v142
	v_fmac_f32_e32 v149, v144, v144
	v_add_f32_e32 v148, v148, v149
	v_mul_f32_e32 v149, v139, v139
	v_fmac_f32_e32 v149, v138, v138
	v_add_f32_e32 v148, v148, v149
	v_mul_f32_e32 v149, v141, v141
	v_fmac_f32_e32 v149, v140, v140
	v_add_f32_e32 v178, v149, v148
	v_mul_f32_e32 v149, v137, v137
	v_mul_f32_e32 v148, v135, v135
	v_fmac_f32_e32 v148, v134, v134
	v_fmac_f32_e32 v149, v136, v136
	v_add_f32_e32 v148, v148, v149
	v_mul_f32_e32 v149, v131, v131
	v_fmac_f32_e32 v149, v130, v130
	v_add_f32_e32 v148, v148, v149
	v_mul_f32_e32 v149, v133, v133
	v_fmac_f32_e32 v149, v132, v132
	v_add_f32_e32 v148, v149, v148
	v_add_f32_e32 v178, v178, v148
	ds_bpermute_b32 v179, v176, v178
	v_pk_mul_f32 v[212:213], v[62:63], v[142:143]
	v_pk_mul_f32 v[214:215], v[64:65], v[144:145]
	v_pk_mul_f32 v[216:217], v[58:59], v[138:139]
	v_pk_mul_f32 v[218:219], v[60:61], v[140:141]
	v_pk_mul_f32 v[220:221], v[46:47], v[134:135]
	v_pk_mul_f32 v[222:223], v[48:49], v[136:137]
	v_pk_mul_f32 v[224:225], v[34:35], v[130:131]
	v_pk_mul_f32 v[226:227], v[36:37], v[132:133]
	s_waitcnt lgkmcnt(0)
	v_add_f32_e32 v178, v178, v179
	ds_bpermute_b32 v248, v177, v178
	v_cvt_pk_bf16_f32 v212, v212, v213
	v_cvt_pk_bf16_f32 v213, v214, v215
	v_cvt_pk_bf16_f32 v214, v216, v217
	v_cvt_pk_bf16_f32 v215, v218, v219
	v_cvt_pk_bf16_f32 v220, v220, v221
	v_cvt_pk_bf16_f32 v221, v222, v223
	v_cvt_pk_bf16_f32 v222, v224, v225
	v_cvt_pk_bf16_f32 v223, v226, v227
	global_store_dwordx4 v175, v[212:215], s[34:35]
	global_store_dwordx4 v175, v[220:223], s[34:35] offset:256
	s_waitcnt lgkmcnt(0)
	v_add_f32_e32 v178, v178, v248
	s_and_saveexec_b64 s[58:59], s[40:41]
	global_store_dword v172, v178, s[50:51]
	s_or_b64 exec, exec, s[58:59]
	s_add_u32 s86, s2, 0x30000
	s_addc_u32 s87, s3, 0
	global_load_dwordx4 v[212:215], v174, s[86:87]
	global_load_dwordx4 v[216:219], v174, s[86:87] offset:16
	global_load_dwordx4 v[220:223], v174, s[86:87] offset:512
	global_load_dwordx4 v[224:227], v174, s[86:87] offset:528
	s_waitcnt vmcnt(15)
	v_pk_add_f32 v[126:127], v[126:127], v[228:229]
	v_pk_add_f32 v[128:129], v[128:129], v[230:231]
	v_pk_add_f32 v[122:123], v[122:123], v[232:233]
	v_pk_add_f32 v[124:125], v[124:125], v[234:235]
	v_pk_add_f32 v[118:119], v[118:119], v[236:237]
	v_pk_add_f32 v[120:121], v[120:121], v[238:239]
	v_pk_add_f32 v[114:115], v[114:115], v[240:241]
	v_pk_add_f32 v[116:117], v[116:117], v[242:243]
	s_add_u32 s88, s16, 0x10000
	s_addc_u32 s89, s17, 0
	s_add_u32 s90, s34, 0x8000
	s_addc_u32 s91, s35, 0
	global_store_dwordx4 v174, v[126:129], s[88:89]
	global_store_dwordx4 v174, v[122:125], s[88:89] offset:16
	global_store_dwordx4 v174, v[118:121], s[88:89] offset:512
	global_store_dwordx4 v174, v[114:117], s[88:89] offset:528
	v_mul_f32_e32 v149, v129, v129
	v_mul_f32_e32 v148, v127, v127
	v_fmac_f32_e32 v148, v126, v126
	v_fmac_f32_e32 v149, v128, v128
	v_add_f32_e32 v148, v148, v149
	v_mul_f32_e32 v149, v123, v123
	v_fmac_f32_e32 v149, v122, v122
	v_add_f32_e32 v148, v148, v149
	v_mul_f32_e32 v149, v125, v125
	v_fmac_f32_e32 v149, v124, v124
	v_add_f32_e32 v178, v149, v148
	v_mul_f32_e32 v149, v121, v121
	v_mul_f32_e32 v148, v119, v119
	v_fmac_f32_e32 v148, v118, v118
	v_fmac_f32_e32 v149, v120, v120
	v_add_f32_e32 v148, v148, v149
	v_mul_f32_e32 v149, v115, v115
	v_fmac_f32_e32 v149, v114, v114
	v_add_f32_e32 v148, v148, v149
	v_mul_f32_e32 v149, v117, v117
	v_fmac_f32_e32 v149, v116, v116
	v_add_f32_e32 v148, v149, v148
	v_add_f32_e32 v178, v178, v148
	ds_bpermute_b32 v179, v176, v178
	v_pk_mul_f32 v[228:229], v[62:63], v[126:127]
	v_pk_mul_f32 v[230:231], v[64:65], v[128:129]
	v_pk_mul_f32 v[232:233], v[58:59], v[122:123]
	v_pk_mul_f32 v[234:235], v[60:61], v[124:125]
	v_pk_mul_f32 v[236:237], v[46:47], v[118:119]
	v_pk_mul_f32 v[238:239], v[48:49], v[120:121]
	v_pk_mul_f32 v[240:241], v[34:35], v[114:115]
	v_pk_mul_f32 v[242:243], v[36:37], v[116:117]
	s_waitcnt lgkmcnt(0)
	v_add_f32_e32 v178, v178, v179
	ds_bpermute_b32 v248, v177, v178
	v_cvt_pk_bf16_f32 v228, v228, v229
	v_cvt_pk_bf16_f32 v229, v230, v231
	v_cvt_pk_bf16_f32 v230, v232, v233
	v_cvt_pk_bf16_f32 v231, v234, v235
	v_cvt_pk_bf16_f32 v236, v236, v237
	v_cvt_pk_bf16_f32 v237, v238, v239
	v_cvt_pk_bf16_f32 v238, v240, v241
	v_cvt_pk_bf16_f32 v239, v242, v243
	global_store_dwordx4 v175, v[228:231], s[90:91]
	global_store_dwordx4 v175, v[236:239], s[90:91] offset:256
	s_waitcnt lgkmcnt(0)
	v_add_f32_e32 v178, v178, v248
	s_and_saveexec_b64 s[58:59], s[40:41]
	global_store_dword v172, v178, s[50:51] offset:64
	s_or_b64 exec, exec, s[58:59]
	s_add_u32 s86, s2, 0x80000
	s_addc_u32 s87, s3, 0
	global_load_dwordx4 v[228:231], v174, s[86:87]
	global_load_dwordx4 v[232:235], v174, s[86:87] offset:16
	global_load_dwordx4 v[236:239], v174, s[86:87] offset:512
	global_load_dwordx4 v[240:243], v174, s[86:87] offset:528
	s_waitcnt vmcnt(22)
	v_pk_add_f32 v[110:111], v[110:111], v[184:185]
	v_pk_add_f32 v[112:113], v[112:113], v[186:187]
	v_pk_add_f32 v[106:107], v[106:107], v[188:189]
	v_pk_add_f32 v[108:109], v[108:109], v[190:191]
	v_pk_add_f32 v[102:103], v[102:103], v[192:193]
	v_pk_add_f32 v[104:105], v[104:105], v[194:195]
	v_pk_add_f32 v[98:99], v[98:99], v[244:245]
	v_pk_add_f32 v[100:101], v[100:101], v[246:247]
	s_add_u32 s88, s16, 0x20000
	s_addc_u32 s89, s17, 0
	s_add_u32 s90, s34, 0x10000
	s_addc_u32 s91, s35, 0
	global_store_dwordx4 v174, v[110:113], s[88:89]
	global_store_dwordx4 v174, v[106:109], s[88:89] offset:16
	global_store_dwordx4 v174, v[102:105], s[88:89] offset:512
	global_store_dwordx4 v174, v[98:101], s[88:89] offset:528
	v_mul_f32_e32 v149, v113, v113
	v_mul_f32_e32 v148, v111, v111
	v_fmac_f32_e32 v148, v110, v110
	v_fmac_f32_e32 v149, v112, v112
	v_add_f32_e32 v148, v148, v149
	v_mul_f32_e32 v149, v107, v107
	v_fmac_f32_e32 v149, v106, v106
	v_add_f32_e32 v148, v148, v149
	v_mul_f32_e32 v149, v109, v109
	v_fmac_f32_e32 v149, v108, v108
	v_add_f32_e32 v178, v149, v148
	v_mul_f32_e32 v149, v105, v105
	v_mul_f32_e32 v148, v103, v103
	v_fmac_f32_e32 v148, v102, v102
	v_fmac_f32_e32 v149, v104, v104
	v_add_f32_e32 v148, v148, v149
	v_mul_f32_e32 v149, v99, v99
	v_fmac_f32_e32 v149, v98, v98
	v_add_f32_e32 v148, v148, v149
	v_mul_f32_e32 v149, v101, v101
	v_fmac_f32_e32 v149, v100, v100
	v_add_f32_e32 v148, v149, v148
	v_add_f32_e32 v178, v178, v148
	ds_bpermute_b32 v179, v176, v178
	v_pk_mul_f32 v[184:185], v[62:63], v[110:111]
	v_pk_mul_f32 v[186:187], v[64:65], v[112:113]
	v_pk_mul_f32 v[188:189], v[58:59], v[106:107]
	v_pk_mul_f32 v[190:191], v[60:61], v[108:109]
	v_pk_mul_f32 v[192:193], v[46:47], v[102:103]
	v_pk_mul_f32 v[194:195], v[48:49], v[104:105]
	v_pk_mul_f32 v[244:245], v[34:35], v[98:99]
	v_pk_mul_f32 v[246:247], v[36:37], v[100:101]
	s_waitcnt lgkmcnt(0)
	v_add_f32_e32 v178, v178, v179
	ds_bpermute_b32 v248, v177, v178
	v_cvt_pk_bf16_f32 v184, v184, v185
	v_cvt_pk_bf16_f32 v185, v186, v187
	v_cvt_pk_bf16_f32 v186, v188, v189
	v_cvt_pk_bf16_f32 v187, v190, v191
	v_cvt_pk_bf16_f32 v192, v192, v193
	v_cvt_pk_bf16_f32 v193, v194, v195
	v_cvt_pk_bf16_f32 v194, v244, v245
	v_cvt_pk_bf16_f32 v195, v246, v247
	global_store_dwordx4 v175, v[184:187], s[90:91]
	global_store_dwordx4 v175, v[192:195], s[90:91] offset:256
	s_waitcnt lgkmcnt(0)
	v_add_f32_e32 v178, v178, v248
	s_and_saveexec_b64 s[58:59], s[40:41]
	global_store_dword v172, v178, s[50:51] offset:128
	s_or_b64 exec, exec, s[58:59]
	s_add_u32 s86, s2, 0x90000
	s_addc_u32 s87, s3, 0
	global_load_dwordx4 v[184:187], v174, s[86:87]
	global_load_dwordx4 v[188:191], v174, s[86:87] offset:16
	global_load_dwordx4 v[192:195], v174, s[86:87] offset:512
	global_load_dwordx4 v[244:247], v174, s[86:87] offset:528
	s_waitcnt vmcnt(22)
	v_pk_add_f32 v[94:95], v[94:95], v[212:213]
	v_pk_add_f32 v[96:97], v[96:97], v[214:215]
	v_pk_add_f32 v[90:91], v[90:91], v[216:217]
	v_pk_add_f32 v[92:93], v[92:93], v[218:219]
	v_pk_add_f32 v[86:87], v[86:87], v[220:221]
	v_pk_add_f32 v[88:89], v[88:89], v[222:223]
	v_pk_add_f32 v[82:83], v[82:83], v[224:225]
	v_pk_add_f32 v[84:85], v[84:85], v[226:227]
	s_add_u32 s88, s16, 0x30000
	s_addc_u32 s89, s17, 0
	s_add_u32 s90, s34, 0x18000
	s_addc_u32 s91, s35, 0
	global_store_dwordx4 v174, v[94:97], s[88:89]
	global_store_dwordx4 v174, v[90:93], s[88:89] offset:16
	global_store_dwordx4 v174, v[86:89], s[88:89] offset:512
	global_store_dwordx4 v174, v[82:85], s[88:89] offset:528
	v_mul_f32_e32 v149, v97, v97
	v_mul_f32_e32 v148, v95, v95
	v_fmac_f32_e32 v148, v94, v94
	v_fmac_f32_e32 v149, v96, v96
	v_add_f32_e32 v148, v148, v149
	v_mul_f32_e32 v149, v91, v91
	v_fmac_f32_e32 v149, v90, v90
	v_add_f32_e32 v148, v148, v149
	v_mul_f32_e32 v149, v93, v93
	v_fmac_f32_e32 v149, v92, v92
	v_add_f32_e32 v178, v149, v148
	v_mul_f32_e32 v149, v89, v89
	v_mul_f32_e32 v148, v87, v87
	v_fmac_f32_e32 v148, v86, v86
	v_fmac_f32_e32 v149, v88, v88
	v_add_f32_e32 v148, v148, v149
	v_mul_f32_e32 v149, v83, v83
	v_fmac_f32_e32 v149, v82, v82
	v_add_f32_e32 v148, v148, v149
	v_mul_f32_e32 v149, v85, v85
	v_fmac_f32_e32 v149, v84, v84
	v_add_f32_e32 v148, v149, v148
	v_add_f32_e32 v178, v178, v148
	ds_bpermute_b32 v179, v176, v178
	v_pk_mul_f32 v[212:213], v[62:63], v[94:95]
	v_pk_mul_f32 v[214:215], v[64:65], v[96:97]
	v_pk_mul_f32 v[216:217], v[58:59], v[90:91]
	v_pk_mul_f32 v[218:219], v[60:61], v[92:93]
	v_pk_mul_f32 v[220:221], v[46:47], v[86:87]
	v_pk_mul_f32 v[222:223], v[48:49], v[88:89]
	v_pk_mul_f32 v[224:225], v[34:35], v[82:83]
	v_pk_mul_f32 v[226:227], v[36:37], v[84:85]
	s_waitcnt lgkmcnt(0)
	v_add_f32_e32 v178, v178, v179
	ds_bpermute_b32 v248, v177, v178
	v_cvt_pk_bf16_f32 v212, v212, v213
	v_cvt_pk_bf16_f32 v213, v214, v215
	v_cvt_pk_bf16_f32 v214, v216, v217
	v_cvt_pk_bf16_f32 v215, v218, v219
	v_cvt_pk_bf16_f32 v220, v220, v221
	v_cvt_pk_bf16_f32 v221, v222, v223
	v_cvt_pk_bf16_f32 v222, v224, v225
	v_cvt_pk_bf16_f32 v223, v226, v227
	global_store_dwordx4 v175, v[212:215], s[90:91]
	global_store_dwordx4 v175, v[220:223], s[90:91] offset:256
	s_waitcnt lgkmcnt(0)
	v_add_f32_e32 v178, v178, v248
	s_and_saveexec_b64 s[58:59], s[40:41]
	global_store_dword v172, v178, s[50:51] offset:192
	s_or_b64 exec, exec, s[58:59]
	s_add_u32 s86, s2, 0xa0000
	s_addc_u32 s87, s3, 0
	global_load_dwordx4 v[212:215], v174, s[86:87]
	global_load_dwordx4 v[216:219], v174, s[86:87] offset:16
	global_load_dwordx4 v[220:223], v174, s[86:87] offset:512
	global_load_dwordx4 v[224:227], v174, s[86:87] offset:528
	s_waitcnt vmcnt(22)
	v_pk_add_f32 v[78:79], v[78:79], v[228:229]
	v_pk_add_f32 v[80:81], v[80:81], v[230:231]
	v_pk_add_f32 v[74:75], v[74:75], v[232:233]
	v_pk_add_f32 v[76:77], v[76:77], v[234:235]
	v_pk_add_f32 v[70:71], v[70:71], v[236:237]
	v_pk_add_f32 v[72:73], v[72:73], v[238:239]
	v_pk_add_f32 v[66:67], v[66:67], v[240:241]
	v_pk_add_f32 v[68:69], v[68:69], v[242:243]
	s_add_u32 s88, s16, 0x80000
	s_addc_u32 s89, s17, 0
	s_add_u32 s90, s34, 0x40000
	s_addc_u32 s91, s35, 0
	global_store_dwordx4 v174, v[78:81], s[88:89]
	global_store_dwordx4 v174, v[74:77], s[88:89] offset:16
	global_store_dwordx4 v174, v[70:73], s[88:89] offset:512
	global_store_dwordx4 v174, v[66:69], s[88:89] offset:528
	v_mul_f32_e32 v149, v81, v81
	v_mul_f32_e32 v148, v79, v79
	v_fmac_f32_e32 v148, v78, v78
	v_fmac_f32_e32 v149, v80, v80
	v_add_f32_e32 v148, v148, v149
	v_mul_f32_e32 v149, v75, v75
	v_fmac_f32_e32 v149, v74, v74
	v_add_f32_e32 v148, v148, v149
	v_mul_f32_e32 v149, v77, v77
	v_fmac_f32_e32 v149, v76, v76
	v_add_f32_e32 v178, v149, v148
	v_mul_f32_e32 v149, v73, v73
	v_mul_f32_e32 v148, v71, v71
	v_fmac_f32_e32 v148, v70, v70
	v_fmac_f32_e32 v149, v72, v72
	v_add_f32_e32 v148, v148, v149
	v_mul_f32_e32 v149, v67, v67
	v_fmac_f32_e32 v149, v66, v66
	v_add_f32_e32 v148, v148, v149
	v_mul_f32_e32 v149, v69, v69
	v_fmac_f32_e32 v149, v68, v68
	v_add_f32_e32 v148, v149, v148
	v_add_f32_e32 v178, v178, v148
	ds_bpermute_b32 v179, v176, v178
	v_pk_mul_f32 v[228:229], v[62:63], v[78:79]
	v_pk_mul_f32 v[230:231], v[64:65], v[80:81]
	v_pk_mul_f32 v[232:233], v[58:59], v[74:75]
	v_pk_mul_f32 v[234:235], v[60:61], v[76:77]
	v_pk_mul_f32 v[236:237], v[46:47], v[70:71]
	v_pk_mul_f32 v[238:239], v[48:49], v[72:73]
	v_pk_mul_f32 v[240:241], v[34:35], v[66:67]
	v_pk_mul_f32 v[242:243], v[36:37], v[68:69]
	s_waitcnt lgkmcnt(0)
	v_add_f32_e32 v178, v178, v179
	ds_bpermute_b32 v248, v177, v178
	v_cvt_pk_bf16_f32 v228, v228, v229
	v_cvt_pk_bf16_f32 v229, v230, v231
	v_cvt_pk_bf16_f32 v230, v232, v233
	v_cvt_pk_bf16_f32 v231, v234, v235
	v_cvt_pk_bf16_f32 v236, v236, v237
	v_cvt_pk_bf16_f32 v237, v238, v239
	v_cvt_pk_bf16_f32 v238, v240, v241
	v_cvt_pk_bf16_f32 v239, v242, v243
	global_store_dwordx4 v175, v[228:231], s[90:91]
	global_store_dwordx4 v175, v[236:239], s[90:91] offset:256
	s_waitcnt lgkmcnt(0)
	v_add_f32_e32 v178, v178, v248
	s_and_saveexec_b64 s[58:59], s[40:41]
	global_store_dword v172, v178, s[50:51] offset:512
	s_or_b64 exec, exec, s[58:59]
	s_add_u32 s86, s2, 0xb0000
	s_addc_u32 s87, s3, 0
	global_load_dwordx4 v[228:231], v174, s[86:87]
	global_load_dwordx4 v[232:235], v174, s[86:87] offset:16
	global_load_dwordx4 v[236:239], v174, s[86:87] offset:512
	global_load_dwordx4 v[240:243], v174, s[86:87] offset:528
	s_waitcnt vmcnt(22)
	v_pk_add_f32 v[54:55], v[54:55], v[184:185]
	v_pk_add_f32 v[56:57], v[56:57], v[186:187]
	v_pk_add_f32 v[50:51], v[50:51], v[188:189]
	v_pk_add_f32 v[52:53], v[52:53], v[190:191]
	v_pk_add_f32 v[42:43], v[42:43], v[192:193]
	v_pk_add_f32 v[44:45], v[44:45], v[194:195]
	v_pk_add_f32 v[38:39], v[38:39], v[244:245]
	v_pk_add_f32 v[40:41], v[40:41], v[246:247]
	s_add_u32 s88, s16, 0x90000
	s_addc_u32 s89, s17, 0
	s_add_u32 s90, s34, 0x48000
	s_addc_u32 s91, s35, 0
	global_store_dwordx4 v174, v[54:57], s[88:89]
	global_store_dwordx4 v174, v[50:53], s[88:89] offset:16
	global_store_dwordx4 v174, v[42:45], s[88:89] offset:512
	global_store_dwordx4 v174, v[38:41], s[88:89] offset:528
	v_mul_f32_e32 v149, v57, v57
	v_mul_f32_e32 v148, v55, v55
	v_fmac_f32_e32 v148, v54, v54
	v_fmac_f32_e32 v149, v56, v56
	v_add_f32_e32 v148, v148, v149
	v_mul_f32_e32 v149, v51, v51
	v_fmac_f32_e32 v149, v50, v50
	v_add_f32_e32 v148, v148, v149
	v_mul_f32_e32 v149, v53, v53
	v_fmac_f32_e32 v149, v52, v52
	v_add_f32_e32 v178, v149, v148
	v_mul_f32_e32 v149, v45, v45
	v_mul_f32_e32 v148, v43, v43
	v_fmac_f32_e32 v148, v42, v42
	v_fmac_f32_e32 v149, v44, v44
	v_add_f32_e32 v148, v148, v149
	v_mul_f32_e32 v149, v39, v39
	v_fmac_f32_e32 v149, v38, v38
	v_add_f32_e32 v148, v148, v149
	v_mul_f32_e32 v149, v41, v41
	v_fmac_f32_e32 v149, v40, v40
	v_add_f32_e32 v148, v149, v148
	v_add_f32_e32 v178, v178, v148
	ds_bpermute_b32 v179, v176, v178
	v_pk_mul_f32 v[184:185], v[62:63], v[54:55]
	v_pk_mul_f32 v[186:187], v[64:65], v[56:57]
	v_pk_mul_f32 v[188:189], v[58:59], v[50:51]
	v_pk_mul_f32 v[190:191], v[60:61], v[52:53]
	v_pk_mul_f32 v[192:193], v[46:47], v[42:43]
	v_pk_mul_f32 v[194:195], v[48:49], v[44:45]
	v_pk_mul_f32 v[244:245], v[34:35], v[38:39]
	v_pk_mul_f32 v[246:247], v[36:37], v[40:41]
	s_waitcnt lgkmcnt(0)
	v_add_f32_e32 v178, v178, v179
	ds_bpermute_b32 v248, v177, v178
	v_cvt_pk_bf16_f32 v184, v184, v185
	v_cvt_pk_bf16_f32 v185, v186, v187
	v_cvt_pk_bf16_f32 v186, v188, v189
	v_cvt_pk_bf16_f32 v187, v190, v191
	v_cvt_pk_bf16_f32 v192, v192, v193
	v_cvt_pk_bf16_f32 v193, v194, v195
	v_cvt_pk_bf16_f32 v194, v244, v245
	v_cvt_pk_bf16_f32 v195, v246, v247
	global_store_dwordx4 v175, v[184:187], s[90:91]
	global_store_dwordx4 v175, v[192:195], s[90:91] offset:256
	s_waitcnt lgkmcnt(0)
	v_add_f32_e32 v178, v178, v248
	s_and_saveexec_b64 s[58:59], s[40:41]
	global_store_dword v172, v178, s[50:51] offset:576
	s_or_b64 exec, exec, s[58:59]
	s_waitcnt vmcnt(18)
	v_pk_add_f32 v[30:31], v[30:31], v[212:213]
	v_pk_add_f32 v[32:33], v[32:33], v[214:215]
	v_pk_add_f32 v[26:27], v[26:27], v[216:217]
	v_pk_add_f32 v[28:29], v[28:29], v[218:219]
	v_pk_add_f32 v[22:23], v[22:23], v[220:221]
	v_pk_add_f32 v[24:25], v[24:25], v[222:223]
	v_pk_add_f32 v[18:19], v[18:19], v[224:225]
	v_pk_add_f32 v[20:21], v[20:21], v[226:227]
	s_add_u32 s88, s16, 0xa0000
	s_addc_u32 s89, s17, 0
	s_add_u32 s90, s34, 0x50000
	s_addc_u32 s91, s35, 0
	global_store_dwordx4 v174, v[30:33], s[88:89]
	global_store_dwordx4 v174, v[26:29], s[88:89] offset:16
	global_store_dwordx4 v174, v[22:25], s[88:89] offset:512
	global_store_dwordx4 v174, v[18:21], s[88:89] offset:528
	v_mul_f32_e32 v149, v33, v33
	v_mul_f32_e32 v148, v31, v31
	v_fmac_f32_e32 v148, v30, v30
	v_fmac_f32_e32 v149, v32, v32
	v_add_f32_e32 v148, v148, v149
	v_mul_f32_e32 v149, v27, v27
	v_fmac_f32_e32 v149, v26, v26
	v_add_f32_e32 v148, v148, v149
	v_mul_f32_e32 v149, v29, v29
	v_fmac_f32_e32 v149, v28, v28
	v_add_f32_e32 v178, v149, v148
	v_mul_f32_e32 v149, v25, v25
	v_mul_f32_e32 v148, v23, v23
	v_fmac_f32_e32 v148, v22, v22
	v_fmac_f32_e32 v149, v24, v24
	v_add_f32_e32 v148, v148, v149
	v_mul_f32_e32 v149, v19, v19
	v_fmac_f32_e32 v149, v18, v18
	v_add_f32_e32 v148, v148, v149
	v_mul_f32_e32 v149, v21, v21
	v_fmac_f32_e32 v149, v20, v20
	v_add_f32_e32 v148, v149, v148
	v_add_f32_e32 v178, v178, v148
	ds_bpermute_b32 v179, v176, v178
	v_pk_mul_f32 v[212:213], v[62:63], v[30:31]
	v_pk_mul_f32 v[214:215], v[64:65], v[32:33]
	v_pk_mul_f32 v[216:217], v[58:59], v[26:27]
	v_pk_mul_f32 v[218:219], v[60:61], v[28:29]
	v_pk_mul_f32 v[220:221], v[46:47], v[22:23]
	v_pk_mul_f32 v[222:223], v[48:49], v[24:25]
	v_pk_mul_f32 v[224:225], v[34:35], v[18:19]
	v_pk_mul_f32 v[226:227], v[36:37], v[20:21]
	s_waitcnt lgkmcnt(0)
	v_add_f32_e32 v178, v178, v179
	ds_bpermute_b32 v248, v177, v178
	v_cvt_pk_bf16_f32 v212, v212, v213
	v_cvt_pk_bf16_f32 v213, v214, v215
	v_cvt_pk_bf16_f32 v214, v216, v217
	v_cvt_pk_bf16_f32 v215, v218, v219
	v_cvt_pk_bf16_f32 v220, v220, v221
	v_cvt_pk_bf16_f32 v221, v222, v223
	v_cvt_pk_bf16_f32 v222, v224, v225
	v_cvt_pk_bf16_f32 v223, v226, v227
	global_store_dwordx4 v175, v[212:215], s[90:91]
	global_store_dwordx4 v175, v[220:223], s[90:91] offset:256
	s_waitcnt lgkmcnt(0)
	v_add_f32_e32 v178, v178, v248
	s_and_saveexec_b64 s[58:59], s[40:41]
	global_store_dword v172, v178, s[50:51] offset:640
	s_or_b64 exec, exec, s[58:59]
	s_waitcnt vmcnt(14)
	v_pk_add_f32 v[14:15], v[14:15], v[228:229]
	v_pk_add_f32 v[16:17], v[16:17], v[230:231]
	v_pk_add_f32 v[10:11], v[10:11], v[232:233]
	v_pk_add_f32 v[12:13], v[12:13], v[234:235]
	v_pk_add_f32 v[6:7], v[6:7], v[236:237]
	v_pk_add_f32 v[8:9], v[8:9], v[238:239]
	v_pk_add_f32 v[2:3], v[2:3], v[240:241]
	v_pk_add_f32 v[4:5], v[4:5], v[242:243]
	s_add_u32 s88, s16, 0xb0000
	s_addc_u32 s89, s17, 0
	s_add_u32 s90, s34, 0x58000
	s_addc_u32 s91, s35, 0
	global_store_dwordx4 v174, v[14:17], s[88:89]
	global_store_dwordx4 v174, v[10:13], s[88:89] offset:16
	global_store_dwordx4 v174, v[6:9], s[88:89] offset:512
	global_store_dwordx4 v174, v[2:5], s[88:89] offset:528
	v_mul_f32_e32 v149, v17, v17
	v_mul_f32_e32 v148, v15, v15
	v_fmac_f32_e32 v148, v14, v14
	v_fmac_f32_e32 v149, v16, v16
	v_add_f32_e32 v148, v148, v149
	v_mul_f32_e32 v149, v11, v11
	v_fmac_f32_e32 v149, v10, v10
	v_add_f32_e32 v148, v148, v149
	v_mul_f32_e32 v149, v13, v13
	v_fmac_f32_e32 v149, v12, v12
	v_add_f32_e32 v178, v149, v148
	v_mul_f32_e32 v149, v9, v9
	v_mul_f32_e32 v148, v7, v7
	v_fmac_f32_e32 v148, v6, v6
	v_fmac_f32_e32 v149, v8, v8
	v_add_f32_e32 v148, v148, v149
	v_mul_f32_e32 v149, v3, v3
	v_fmac_f32_e32 v149, v2, v2
	v_add_f32_e32 v148, v148, v149
	v_mul_f32_e32 v149, v5, v5
	v_fmac_f32_e32 v149, v4, v4
	v_add_f32_e32 v148, v149, v148
	v_add_f32_e32 v178, v178, v148
	ds_bpermute_b32 v179, v176, v178
	v_pk_mul_f32 v[228:229], v[62:63], v[14:15]
	v_pk_mul_f32 v[230:231], v[64:65], v[16:17]
	v_pk_mul_f32 v[232:233], v[58:59], v[10:11]
	v_pk_mul_f32 v[234:235], v[60:61], v[12:13]
	v_pk_mul_f32 v[236:237], v[46:47], v[6:7]
	v_pk_mul_f32 v[238:239], v[48:49], v[8:9]
	v_pk_mul_f32 v[240:241], v[34:35], v[2:3]
	v_pk_mul_f32 v[242:243], v[36:37], v[4:5]
	s_waitcnt lgkmcnt(0)
	v_add_f32_e32 v178, v178, v179
	ds_bpermute_b32 v248, v177, v178
	v_cvt_pk_bf16_f32 v228, v228, v229
	v_cvt_pk_bf16_f32 v229, v230, v231
	v_cvt_pk_bf16_f32 v230, v232, v233
	v_cvt_pk_bf16_f32 v231, v234, v235
	v_cvt_pk_bf16_f32 v236, v236, v237
	v_cvt_pk_bf16_f32 v237, v238, v239
	v_cvt_pk_bf16_f32 v238, v240, v241
	v_cvt_pk_bf16_f32 v239, v242, v243
	global_store_dwordx4 v175, v[228:231], s[90:91]
	global_store_dwordx4 v175, v[236:239], s[90:91] offset:256
	s_waitcnt lgkmcnt(0)
	v_add_f32_e32 v178, v178, v248
	s_and_saveexec_b64 s[58:59], s[40:41]
	global_store_dword v172, v178, s[50:51] offset:704
	s_or_b64 exec, exec, s[58:59]
	s_andn2_b64 vcc, exec, s[42:43]
	s_mov_b64 s[42:43], -1
	s_cbranch_vccnz .LBB0_734
	s_andn2_b64 vcc, exec, s[0:1]
	s_cbranch_vccnz .LBB0_733
	s_barrier
	s_branch .LBB0_733
